# unit-order rotation also in P8/P9 (all five exact-round split-K phases): odd XCDs take the K-eighth sub-unit first
# speedup vs baseline: 1.0206x; 1.0118x over previous
.LBB0_1117:
	s_cmp_lt_i32 s92, 9
	s_cselect_b64 s[0:1], -1, 0
	s_cmp_gt_i32 s93, 8
	s_cselect_b64 s[2:3], -1, 0
	s_and_b64 s[0:1], s[0:1], s[2:3]
	s_andn2_b64 vcc, exec, s[0:1]
	s_cbranch_vccnz .LBB0_1219
	s_cmpk_lg_i32 s33, 0x100
	s_cbranch_scc1 .Lrot8_f
	v_readlane_b32 s0, v254, 15
	s_nop 3
	s_bitcmp1_b32 s0, 5
	s_cbranch_scc0 .Lrot8_f
	s_add_i32 s95, s95, 0x200
.Lrot8_f:
	s_waitcnt vmcnt(31)
	v_mbcnt_lo_u32_b32 v0, -1, 0
	v_mbcnt_hi_u32_b32 v0, -1, v0
	s_movk_i32 s2, 0x800
	v_mbcnt_lo_u32_b32 v0, -1, 0
	v_mbcnt_hi_u32_b32 v0, -1, v0
	s_ashr_i32 s0, s2, 31
	s_lshr_b32 s0, s0, 26
	s_add_i32 s2, s2, s0
	s_cmpk_gt_i32 s95, 0x1ff
	s_cbranch_scc0 .LBB0_1209
	s_add_i32 s6, s95, 0xfffffe00
	s_cmpk_gt_u32 s6, 0xff
	s_mov_b64 s[10:11], 0
	s_cbranch_scc1 .LBB0_1211
	s_lshl_b32 s0, s95, 9
	s_and_b32 s7, s0, 0xe00
	s_lshr_b32 s0, s6, 7
	s_or_b32 s38, s0, 32
	s_bfe_u32 s25, s95, 0x40003
	s_mov_b32 s39, 4
	s_mov_b64 s[0:1], -1
	s_andn2_b64 vcc, exec, s[10:11]
	s_ashr_i32 s2, s2, 6
	s_cbranch_vccz .LBB0_1212

.LBB0_1124:
	s_add_i32 s42, s3, 0x18000
	s_or_b32 s1, s22, 0x80
	s_mov_b32 s14, s10
	s_mov_b32 s15, s11
	s_mov_b32 m0, s42
	s_add_i32 s43, s3, 0x1a000
	s_waitcnt vmcnt(2)
	s_barrier
	buffer_load_dwordx4 v177, s[12:15], s1 offen lds
	s_mov_b32 m0, s43
	s_add_i32 s44, s3, 0x8000
	buffer_load_dwordx4 v179, s[12:15], s1 offen lds
	s_or_b32 s1, s23, 0x80
	s_mov_b32 m0, s44
	s_add_i32 s45, s3, 0xa000
	buffer_load_dwordx4 v176, s[8:11], s1 offen lds
	s_mov_b32 m0, s45
	s_add_i32 s46, s3, 0x1c000
	buffer_load_dwordx4 v178, s[8:11], s1 offen lds
	s_or_b32 s1, s22, 0x80080
	s_mov_b32 m0, s46
	s_add_i32 s47, s3, 0x1e000
	buffer_load_dwordx4 v177, s[12:15], s1 offen lds
	s_mov_b32 m0, s47
	s_lshl_b32 s49, s0, 6
	buffer_load_dwordx4 v179, s[12:15], s1 offen lds
	v_ashrrev_i32_e32 v1, 6, v0
	s_lshl_b32 s0, s0, 13
	v_and_b32_e32 v2, 48, v0
	v_lshl_add_u32 v3, v1, 10, s0
	v_lshlrev_b32_e32 v4, 6, v0
	s_movk_i32 s0, 0x3c0
	v_and_or_b32 v2, v4, s0, v2
	v_readlane_b32 s0, v254, 16
	s_lshl_b32 s0, s0, 5
	s_and_b32 s50, s0, 0x60
	v_lshlrev_b32_e32 v0, 2, v0
	s_lshr_b32 s0, s50, 3
	v_and_b32_e32 v0, 32, v0
	v_add_lshl_u32 v1, v1, s0, 10
	v_bitop3_b32 v3, v2, v3, v0 bitop3:0xde
	v_bitop3_b32 v0, v2, v1, v0 bitop3:0xde
	s_waitcnt vmcnt(6)
	s_add_i32 s51, s3, 0xc000
	s_cmpk_lt_u32 s89, 0x100
	v_add_u32_e32 v0, 0, v0
	s_cselect_b64 s[18:19], -1, 0
	s_add_i32 s52, s3, 0xe000
	s_ashr_i32 s53, s33, 31
	s_ashr_i32 s56, s95, 31
	v_mov_b64_e32 v[156:157], 0x1ff
	s_cmpk_lg_i32 s33, 0x100
	s_cbranch_scc1 .Lrot8_r
	v_readlane_b32 s0, v254, 15
	s_nop 3
	s_bitcmp1_b32 s0, 5
	s_cbranch_scc0 .Lrot8_r
	s_sub_i32 s95, s95, 0x200
.Lrot8_r:
	v_add_u32_e32 v180, 0x10000, v0
	v_add_u32_e32 v181, 0x14000, v0
	v_add_u32_e32 v182, 0, v3
	v_add_u32_e32 v183, 0x18000, v0
	v_add_u32_e32 v184, 0x1c000, v0
	v_mov_b32_e32 v159, 0
	s_lshl_b32 s24, s50, 2
	s_mov_b32 s57, s7
	s_barrier
	s_branch .LBB0_1127

.LBB0_1127:
	s_add_i32 s57, s57, 1
	s_mul_i32 s0, s57, s53
	s_mul_hi_u32 s1, s57, s33
	s_add_i32 s1, s1, s0
	s_mul_i32 s0, s57, s33
	s_add_u32 s0, s0, s95
	s_addc_u32 s1, s1, s56
	s_cmpk_lg_i32 s33, 0x100
	s_cbranch_scc1 .Lrot8_h
	v_readlane_b32 s14, v254, 15
	s_nop 3
	s_bitcmp1_b32 s14, 5
	s_cbranch_scc0 .Lrot8_h
	s_cmp_lg_u32 s1, 0
	s_cbranch_scc1 .Lrot8_h
	s_cmpk_ge_u32 s0, 0x300
	s_cbranch_scc1 .Lrot8_h
	s_add_u32 s0, s0, 0x200
	s_cmpk_lt_u32 s0, 0x300
	s_cbranch_scc1 .Lrot8_h
	s_sub_u32 s0, s0, 0x300
.Lrot8_h:
	v_cmp_gt_i64_e32 vcc, s[0:1], v[156:157]
	s_mov_b64 s[14:15], -1
	s_cbranch_vccz .LBB0_1130
	s_add_i32 s1, s0, 0xfffffe00
	s_mov_b64 s[14:15], 0
	s_cmpk_gt_i32 s1, 0xff
	s_mov_b64 s[26:27], 0
	s_cbranch_scc1 .LBB0_1130
	s_lshl_b32 s26, s0, 2
	s_and_b32 s58, s26, 28
	s_ashr_i32 s26, s1, 3
	s_lshr_b32 s27, s26, 28
	s_add_i32 s27, s26, s27
	s_ashr_i32 s62, s27, 4
	s_and_b32 s27, s27, -16
	s_mov_b32 s59, 4
	s_add_i32 s63, s62, 32
	s_sub_i32 s62, s26, s27
	s_mov_b64 s[26:27], -1
	s_mov_b32 s64, s1

.LBB0_1219:
	s_cmp_lt_i32 s92, 10
	s_cselect_b64 s[0:1], -1, 0
	s_cmp_gt_i32 s93, 9
	s_cselect_b64 s[2:3], -1, 0
	s_and_b64 s[0:1], s[0:1], s[2:3]
	s_andn2_b64 vcc, exec, s[0:1]
	s_cbranch_vccnz .LBB0_1372
	s_cmpk_lg_i32 s33, 0x100
	s_cbranch_scc1 .Lrot9_f
	v_readlane_b32 s0, v254, 15
	s_nop 3
	s_bitcmp1_b32 s0, 5
	s_cbranch_scc0 .Lrot9_f
	s_add_i32 s95, s95, 0x200
.Lrot9_f:
	s_movk_i32 s3, 0x1000
	v_mbcnt_lo_u32_b32 v180, -1, 0
	v_mbcnt_hi_u32_b32 v180, -1, v180
	s_waitcnt vmcnt(31)
	v_mbcnt_lo_u32_b32 v0, -1, 0
	v_mbcnt_hi_u32_b32 v0, -1, v0
	s_ashr_i32 s0, s3, 31
	s_lshr_b32 s0, s0, 26
	s_add_i32 s3, s3, s0
	s_cmpk_gt_i32 s95, 0x1ff
	s_cbranch_scc0 .LBB0_1226
	s_add_i32 s0, s95, 0xfffffe00
	s_mov_b64 s[8:9], 0
	s_cmpk_lt_u32 s0, 0x100
	s_mov_b64 s[6:7], 0
	s_cbranch_scc0 .LBB0_1223
	s_lshr_b32 s1, s0, 3
	s_cmpk_gt_u32 s0, 0x7f
	s_cselect_b32 s15, 33, 32
	s_add_i32 s2, s1, -16
	s_cmpk_lt_u32 s0, 0x80
	s_cselect_b32 s2, s1, s2
	s_lshl_b32 s1, s95, 10
	s_and_b32 s1, s1, 0x1c00
	s_mov_b64 s[6:7], -1
	s_ashr_i32 s3, s3, 6
	s_mov_b32 s20, 8
	s_and_b64 vcc, exec, s[8:9]
	s_cbranch_vccz .LBB0_1227
	s_branch .LBB0_1224

.LBB0_1233:
	s_add_u32 s42, s34, 0x26d00000
	s_addc_u32 s43, s35, 0
	s_add_i32 s45, s21, 0x18000
	s_or_b32 s11, s75, 0x80
	s_mov_b32 s82, s6
	s_mov_b32 s83, s7
	s_mov_b32 m0, s45
	s_add_i32 s46, s21, 0x1a000
	s_waitcnt vmcnt(2)
	s_barrier
	buffer_load_dwordx4 v182, s[80:83], s11 offen lds
	s_mov_b32 m0, s46
	s_add_i32 s47, s21, 0x8000
	buffer_load_dwordx4 v184, s[80:83], s11 offen lds
	s_or_b32 s11, s59, 0x80
	s_mov_b32 m0, s47
	s_add_i32 s49, s21, 0xa000
	buffer_load_dwordx4 v181, s[4:7], s11 offen lds
	s_mov_b32 m0, s49
	s_add_i32 s50, s21, 0x1c000
	buffer_load_dwordx4 v183, s[4:7], s11 offen lds
	s_or_b32 s11, s75, 0x100080
	s_mov_b32 m0, s50
	s_add_i32 s51, s21, 0x1e000
	buffer_load_dwordx4 v182, s[80:83], s11 offen lds
	s_mov_b32 m0, s51
	s_lshl_b32 s44, s10, 6
	buffer_load_dwordx4 v184, s[80:83], s11 offen lds
	v_ashrrev_i32_e32 v1, 6, v0
	s_lshl_b32 s10, s10, 13
	v_and_b32_e32 v2, 48, v0
	v_lshl_add_u32 v3, v1, 10, s10
	v_lshlrev_b32_e32 v4, 6, v0
	s_movk_i32 s10, 0x3c0
	v_and_or_b32 v2, v4, s10, v2
	v_readlane_b32 s10, v254, 16
	s_lshl_b32 s10, s10, 5
	s_and_b32 s52, s10, 0x60
	v_lshlrev_b32_e32 v0, 2, v0
	s_lshr_b32 s10, s52, 3
	v_and_b32_e32 v0, 32, v0
	v_add_lshl_u32 v1, v1, s10, 10
	v_bitop3_b32 v3, v2, v3, v0 bitop3:0xde
	v_bitop3_b32 v0, v2, v1, v0 bitop3:0xde
	s_waitcnt vmcnt(6)
	s_add_i32 s57, s21, 0xc000
	s_cmpk_lt_u32 s89, 0x100
	v_add_u32_e32 v0, 0, v0
	s_mov_b32 s53, 0x8000
	s_mov_b32 s56, 0xc000
	s_cselect_b64 s[10:11], -1, 0
	s_add_i32 s54, s21, 0xe000
	s_ashr_i32 s55, s33, 31
	s_ashr_i32 s64, s95, 31
	v_mov_b64_e32 v[156:157], 0x1ff
	s_cmpk_lg_i32 s33, 0x100
	s_cbranch_scc1 .Lrot9_r
	v_readlane_b32 s12, v254, 15
	s_nop 3
	s_bitcmp1_b32 s12, 5
	s_cbranch_scc0 .Lrot9_r
	s_sub_i32 s95, s95, 0x200
.Lrot9_r:
	v_add_u32_e32 v185, 0x10000, v0
	v_add_u32_e32 v186, 0x14000, v0
	v_add_u32_e32 v187, 0, v3
	v_add_u32_e32 v188, 0x18000, v0
	v_add_u32_e32 v189, 0x1c000, v0
	s_mov_b64 s[12:13], 0x2000
	v_mov_b32_e32 v159, 0
	s_lshl_b32 s14, s52, 2
	s_mov_b32 s65, 0x24000
	s_mov_b32 s66, 0x28000
	s_mov_b32 s67, 0x2c000
	s_mov_b32 s68, s1
	s_barrier
	s_branch .LBB0_1236

.LBB0_1236:
	s_add_i32 s68, s68, 1
	s_mul_i32 s16, s68, s55
	s_mul_hi_u32 s17, s68, s33
	s_add_i32 s17, s17, s16
	s_mul_i32 s16, s68, s33
	s_add_u32 s18, s16, s95
	s_addc_u32 s19, s17, s64
	s_cmpk_lg_i32 s33, 0x100
	s_cbranch_scc1 .Lrot9_h
	v_readlane_b32 s23, v254, 15
	s_nop 3
	s_bitcmp1_b32 s23, 5
	s_cbranch_scc0 .Lrot9_h
	s_cmp_lg_u32 s19, 0
	s_cbranch_scc1 .Lrot9_h
	s_cmpk_ge_u32 s18, 0x300
	s_cbranch_scc1 .Lrot9_h
	s_add_u32 s18, s18, 0x200
	s_cmpk_lt_u32 s18, 0x300
	s_cbranch_scc1 .Lrot9_h
	s_sub_u32 s18, s18, 0x300
.Lrot9_h:
	v_cmp_gt_i64_e32 vcc, s[18:19], v[156:157]
	s_mov_b64 s[24:25], -1
	s_cbranch_vccz .LBB0_1239
	s_add_i32 s19, s18, 0xfffffe00
	s_mov_b64 s[24:25], 0
	s_cmpk_gt_i32 s19, 0xff
	s_mov_b64 s[16:17], 0
	s_cbranch_scc1 .LBB0_1239
	s_lshl_b32 s16, s18, 3
	s_and_b32 s69, s16, 56
	s_ashr_i32 s16, s19, 3
	s_lshr_b32 s17, s16, 28
	s_add_i32 s17, s16, s17
	s_ashr_i32 s22, s17, 4
	s_and_b32 s17, s17, -16
	s_add_i32 s71, s22, 32
	s_sub_i32 s70, s16, s17
	s_mov_b32 s73, 8
	s_mov_b64 s[16:17], -1
	s_mov_b32 s74, s19
